# t21 + grid barriers: non-leader workgroups invalidate only their L1 (buffer_inv sc0); the XCD leader already invalidates L2 before releasing them
# speedup vs baseline: 1.0099x; 1.0099x over previous
.LBB0_172:
	s_or_b64 exec, exec, s[10:11]
	s_waitcnt vmcnt(0)
	buffer_inv sc0
	s_waitcnt vmcnt(0)

.LBB0_490:
	s_or_b64 exec, exec, s[8:9]
	s_waitcnt vmcnt(0)
	buffer_inv sc0
	s_waitcnt vmcnt(0)
